# attention C loop: last two PV MFMAs carried across the barrier to cover K-fragment LDS latency; row-sum adds spread over PV slots; writes 2 slots earlier
# speedup vs baseline: 1.0086x; 1.0018x over previous
.LBB0_739:
	s_lshl_b32 s8, s56, 5
	s_add_i32 s8, s8, s55
	v_readlane_b32 s18, v254, 6
	s_or_b32 s8, s8, s54
	v_readlane_b32 s19, v254, 7
	s_and_b64 s[18:19], s[18:19], exec
	s_cselect_b32 s58, s8, s45
	s_ashr_i32 s18, s58, 6
	s_lshl_b32 s8, s58, 7
	s_ashr_i32 s19, s18, 31
	s_and_b32 s8, s8, 0x780
	s_lshl_b64 s[40:41], s[18:19], 20
	s_lshl_b64 s[42:43], s[18:19], 21
	s_add_u32 s17, s12, s42
	s_addc_u32 s18, s13, s43
	s_lshl_b32 s19, s58, 3
	s_and_b32 s57, s19, 0x180
	s_lshl_b32 s22, s57, 1
	s_add_u32 s17, s17, s22
	s_addc_u32 s19, s18, 0
	s_add_u32 s18, s17, s38
	s_addc_u32 s19, s19, s39
	s_add_u32 s17, s48, s42
	s_addc_u32 s21, s49, s43
	s_add_u32 s20, s17, s22
	s_addc_u32 s21, s21, 0
	s_add_u32 s17, s50, s42
	s_addc_u32 s23, s51, s43
	s_add_u32 s22, s17, s22
	s_addc_u32 s23, s23, 0
	v_lshl_add_u64 v[0:1], s[20:21], 0, v[216:217]
	v_lshl_add_u64 v[2:3], s[20:21], 0, v[220:221]
	v_lshl_add_u64 v[8:9], s[22:23], 0, v[216:217]
	v_lshl_add_u64 v[10:11], s[22:23], 0, v[220:221]
	v_lshl_add_u64 v[0:1], v[0:1], 0, v[218:219]
	v_lshl_add_u64 v[4:5], v[2:3], 0, v[222:223]
	v_lshl_add_u64 v[8:9], v[8:9], 0, v[218:219]
	v_lshl_add_u64 v[12:13], v[10:11], 0, v[222:223]
	global_load_dwordx4 v[0:3], v[0:1], off
	s_nop 0
	global_load_dwordx4 v[4:7], v[4:5], off
	s_nop 0
	global_load_dwordx4 v[8:11], v[8:9], off
	s_nop 0
	global_load_dwordx4 v[12:15], v[12:13], off
	v_or_b32_e32 v16, s8, v233
	v_lshlrev_b32_e32 v192, 10, v16
	v_lshl_add_u64 v[16:17], s[18:19], 0, v[192:193]
	v_mov_b32_e32 v215, v193
	v_lshl_add_u64 v[16:17], v[16:17], 0, v[214:215]
	global_load_dwordx4 v[160:163], v[16:17], off
	global_load_dwordx4 v[164:167], v[16:17], off offset:32
	global_load_dwordx4 v[168:171], v[16:17], off offset:64
	global_load_dwordx4 v[172:175], v[16:17], off offset:96
	v_lshl_add_u64 v[16:17], s[20:21], 0, v[196:197]
	v_lshl_add_u64 v[18:19], s[20:21], 0, v[198:199]
	v_lshl_add_u64 v[16:17], v[16:17], 0, v[218:219]
	v_lshl_add_u64 v[18:19], v[18:19], 0, v[222:223]
	global_load_dwordx4 v[176:179], v[16:17], off
	global_load_dwordx4 v[180:183], v[18:19], off
	v_add_u32_e32 v192, v202, v234
	v_add_u32_e32 v215, v204, v235
	v_add_u32_e32 v243, v206, v234
	v_add_u32_e32 v244, v208, v235
	s_mov_b32 s17, s16
	s_mov_b32 s18, s16
	s_mov_b32 s19, s16
	s_mov_b32 s20, s16
	s_mov_b32 s21, s16
	s_mov_b32 s22, s16
	s_mov_b32 s23, s16
	s_mov_b32 s24, s16
	s_mov_b32 s25, s16
	s_mov_b32 s26, s16
	s_mov_b32 s27, s16
	s_mov_b32 s28, s16
	s_mov_b32 s29, s16
	s_mov_b32 s30, s16
	s_mov_b32 s31, s16
	v_mov_b32_e32 v246, 0
	v_mov_b32_e32 v245, 0xf149f2ca
	s_waitcnt vmcnt(9)
	ds_write_b128 v192, v[0:3]
	s_waitcnt vmcnt(8)
	ds_write_b128 v215, v[4:7]
	s_waitcnt vmcnt(7)
	ds_write_b128 v243, v[8:11] offset:34816
	s_waitcnt vmcnt(6)
	ds_write_b128 v244, v[12:15] offset:34816
	s_waitcnt lgkmcnt(0)
	s_barrier
	ds_read_b128 v[0:3], v240
	ds_read_b128 v[4:7], v240 offset:32
	s_waitcnt vmcnt(5) lgkmcnt(1)
	v_mfma_f32_32x32x16_bf16 v[80:95], v[0:3], v[160:163], 0
	ds_read_b128 v[0:3], v240 offset:8704
	ds_read_b128 v[8:11], v240 offset:8736
	s_waitcnt lgkmcnt(1)
	v_mfma_f32_32x32x16_bf16 v[64:79], v[0:3], v[160:163], 0
	ds_read_b128 v[0:3], v240 offset:64
	s_waitcnt vmcnt(4)
	v_mfma_f32_32x32x16_bf16 v[80:95], v[4:7], v[164:167], v[80:95]
	ds_read_b128 v[4:7], v240 offset:8768
	ds_read_b128 v[16:19], v240 offset:96
	ds_read_b128 v[20:23], v240 offset:8800
	s_waitcnt vmcnt(1)
	ds_write_b128 v241, v[176:179] offset:17408
	s_waitcnt vmcnt(0)
	ds_write_b128 v242, v[180:183] offset:17408
	s_waitcnt lgkmcnt(0)
	s_barrier
	v_mfma_f32_32x32x16_bf16 v[64:79], v[8:11], v[164:167], v[64:79]
	v_mfma_f32_32x32x16_bf16 v[80:95], v[0:3], v[168:171], v[80:95]
	v_mfma_f32_32x32x16_bf16 v[64:79], v[4:7], v[168:171], v[64:79]
	v_mov_b64_e32 v[0:1], s[16:17]
	v_mov_b64_e32 v[2:3], s[18:19]
	v_mov_b64_e32 v[4:5], s[20:21]
	v_mov_b64_e32 v[6:7], s[22:23]
	v_mov_b64_e32 v[8:9], s[24:25]
	v_mov_b64_e32 v[10:11], s[26:27]
	v_mov_b64_e32 v[12:13], s[28:29]
	v_mfma_f32_32x32x16_bf16 v[80:95], v[16:19], v[172:175], v[80:95]
	v_mov_b64_e32 v[14:15], s[30:31]
	s_lshl_b32 s17, s58, 4
	s_and_b32 s17, s17, 0x300
	s_or_b32 s42, s42, s17
	v_mov_b64_e32 v[46:47], v[14:15]
	v_mov_b64_e32 v[62:63], v[14:15]
	v_lshl_add_u64 v[224:225], v[210:211], 0, s[42:43]
	v_mfma_f32_32x32x16_bf16 v[64:79], v[20:23], v[172:175], v[64:79]
	v_mov_b64_e32 v[30:31], v[14:15]
	v_lshl_add_u64 v[226:227], v[212:213], 0, s[42:43]
	s_mov_b64 s[18:19], 0
	v_mov_b64_e32 v[28:29], v[12:13]
	v_mov_b64_e32 v[26:27], v[10:11]
	v_mov_b64_e32 v[24:25], v[8:9]
	v_mov_b64_e32 v[22:23], v[6:7]
	v_mov_b64_e32 v[20:21], v[4:5]
	v_mov_b64_e32 v[18:19], v[2:3]
	v_mov_b64_e32 v[16:17], v[0:1]
	v_mov_b64_e32 v[44:45], v[12:13]
	v_mov_b64_e32 v[42:43], v[10:11]
	v_mov_b64_e32 v[40:41], v[8:9]
	v_mov_b64_e32 v[38:39], v[6:7]
	v_mov_b64_e32 v[36:37], v[4:5]
	v_mov_b64_e32 v[34:35], v[2:3]
	v_mov_b64_e32 v[32:33], v[0:1]
	v_mov_b64_e32 v[60:61], v[12:13]
	v_mov_b64_e32 v[58:59], v[10:11]
	v_mov_b64_e32 v[56:57], v[8:9]
	v_mov_b64_e32 v[54:55], v[6:7]
	v_mov_b64_e32 v[52:53], v[4:5]
	v_mov_b64_e32 v[50:51], v[2:3]
	v_mov_b64_e32 v[48:49], v[0:1]
	v_readfirstlane_b32 s98, v226
	v_readfirstlane_b32 s99, v227
	s_nop 3
	v_subrev_u32_e32 v247, s98, v226
	v_add_u32_e32 v252, 0x8000, v247
	v_add_u32_e32 v253, 0x10000, v247
	v_add_u32_e32 v245, 0x18000, v247
	s_add_u32 s100, s98, 0xbf10000
	s_addc_u32 s101, s99, 0
	s_add_u32 s98, s98, 0xaf20000
	s_addc_u32 s99, s99, 0
	s_mov_b32 s17, 0
	v_mov_b32_e32 v140, 0
	v_mov_b32_e32 v141, 0
	v_mov_b32_e32 v142, 0
	v_mov_b32_e32 v143, 0
	v_mov_b32_e32 v156, 0
	v_mov_b32_e32 v157, 0
	v_mov_b32_e32 v158, 0
	v_mov_b32_e32 v159, 0
	v_mov_b32_e32 v228, 0
	v_mov_b32_e32 v229, 0
	v_mov_b32_e32 v230, 0
	v_mov_b32_e32 v231, 0

.LBB0_742:
	ds_read_b128 v[96:99], v240 offset:17408
	ds_read_b128 v[144:147], v240 offset:26112
	ds_read_b128 v[148:151], v240 offset:17440
	ds_read_b128 v[152:155], v240 offset:26144
	v_mfma_f32_32x32x16_bf16 v[16:31], v[156:159], v[140:143], v[16:31]
	v_mfma_f32_32x32x16_bf16 v[0:15], v[228:231], v[140:143], v[0:15]
	ds_read_b128 v[156:159], v240 offset:17472
	ds_read_b128 v[228:231], v240 offset:26176
	global_load_dwordx4 v[184:187], v247, s[100:101]
	global_load_dwordx4 v[188:191], v252, s[100:101]
	s_waitcnt lgkmcnt(5)
	v_mfma_f32_32x32x16_bf16 v[112:127], v[96:99], v[160:163], 0
	v_exp_f32_e32 v80, v80
	v_exp_f32_e32 v81, v81
	s_waitcnt lgkmcnt(4)
	v_mfma_f32_32x32x16_bf16 v[96:111], v[144:147], v[160:163], 0
	ds_read_b128 v[144:147], v240 offset:17504
	v_exp_f32_e32 v82, v82
	v_exp_f32_e32 v83, v83
	s_waitcnt lgkmcnt(4)
	v_mfma_f32_32x32x16_bf16 v[112:127], v[148:151], v[164:167], v[112:127]
	ds_read_b128 v[148:151], v240 offset:26208
	v_exp_f32_e32 v84, v84
	v_exp_f32_e32 v85, v85
	s_waitcnt lgkmcnt(4)
	v_mfma_f32_32x32x16_bf16 v[96:111], v[152:155], v[164:167], v[96:111]
	v_exp_f32_e32 v86, v86
	v_exp_f32_e32 v87, v87
	v_cvt_pk_bf16_f32 v128, v80, v81
	v_cvt_pk_bf16_f32 v129, v82, v83
	s_waitcnt lgkmcnt(3)
	v_mfma_f32_32x32x16_bf16 v[112:127], v[156:159], v[168:171], v[112:127]
	ds_read_b64_tr_b16 v[152:153], v207 offset:34816
	ds_read_b64_tr_b16 v[154:155], v207 offset:37376
	v_exp_f32_e32 v88, v88
	v_exp_f32_e32 v89, v89
	v_cvt_pk_bf16_f32 v130, v84, v85
	v_cvt_pk_bf16_f32 v131, v86, v87
	s_waitcnt lgkmcnt(4)
	v_mfma_f32_32x32x16_bf16 v[96:111], v[228:231], v[168:171], v[96:111]
	ds_read_b64_tr_b16 v[156:157], v207 offset:34880
	ds_read_b64_tr_b16 v[158:159], v207 offset:37440
	v_exp_f32_e32 v90, v90
	v_exp_f32_e32 v91, v91
	s_waitcnt lgkmcnt(5)
	v_mfma_f32_32x32x16_bf16 v[112:127], v[144:147], v[172:175], v[112:127]
	ds_read_b64_tr_b16 v[228:229], v207 offset:34944
	ds_read_b64_tr_b16 v[230:231], v207 offset:37504
	v_exp_f32_e32 v92, v92
	v_exp_f32_e32 v93, v93
	s_waitcnt lgkmcnt(6)
	v_mfma_f32_32x32x16_bf16 v[96:111], v[148:151], v[172:175], v[96:111]
	ds_read_b64_tr_b16 v[144:145], v207 offset:35008
	ds_read_b64_tr_b16 v[146:147], v207 offset:37568
	v_exp_f32_e32 v94, v94
	v_exp_f32_e32 v95, v95
	v_cvt_pk_bf16_f32 v132, v88, v89
	v_cvt_pk_bf16_f32 v133, v90, v91
	s_waitcnt lgkmcnt(6)
	v_mfma_f32_32x32x16_bf16 v[48:63], v[152:155], v[128:131], v[48:63]
	ds_read_b64_tr_b16 v[148:149], v207 offset:39936
	ds_read_b64_tr_b16 v[150:151], v207 offset:42496
	v_cvt_pk_bf16_f32 v134, v92, v93
	v_cvt_pk_bf16_f32 v135, v94, v95
	v_exp_f32_e32 v64, v64
	v_exp_f32_e32 v65, v65
	s_waitcnt lgkmcnt(6)
	v_mfma_f32_32x32x16_bf16 v[32:47], v[156:159], v[128:131], v[32:47]
	ds_read_b64_tr_b16 v[152:153], v207 offset:40000
	ds_read_b64_tr_b16 v[154:155], v207 offset:42560
	v_exp_f32_e32 v66, v66
	v_exp_f32_e32 v67, v67
	v_add_f32_e32 v80, v80, v81
	v_add_f32_e32 v82, v82, v83
	s_waitcnt lgkmcnt(6)
	v_mfma_f32_32x32x16_bf16 v[16:31], v[228:231], v[128:131], v[16:31]
	ds_read_b64_tr_b16 v[156:157], v207 offset:40064
	ds_read_b64_tr_b16 v[158:159], v207 offset:42624
	v_exp_f32_e32 v68, v68
	v_exp_f32_e32 v69, v69
	v_add_f32_e32 v84, v84, v85
	v_add_f32_e32 v86, v86, v87
	s_waitcnt lgkmcnt(6)
	v_mfma_f32_32x32x16_bf16 v[0:15], v[144:147], v[128:131], v[0:15]
	ds_read_b64_tr_b16 v[228:229], v207 offset:40128
	ds_read_b64_tr_b16 v[230:231], v207 offset:42688
	v_exp_f32_e32 v70, v70
	v_exp_f32_e32 v71, v71
	v_add_f32_e32 v88, v88, v89
	v_add_f32_e32 v90, v90, v91
	s_waitcnt lgkmcnt(6)
	v_mfma_f32_32x32x16_bf16 v[48:63], v[148:151], v[132:135], v[48:63]
	ds_read_b64_tr_b16 v[144:145], v207 offset:45056
	ds_read_b64_tr_b16 v[146:147], v207 offset:47616
	v_cvt_pk_bf16_f32 v136, v64, v65
	v_cvt_pk_bf16_f32 v137, v66, v67
	v_cvt_pk_bf16_f32 v138, v68, v69
	v_cvt_pk_bf16_f32 v139, v70, v71
	v_exp_f32_e32 v72, v72
	s_waitcnt lgkmcnt(6)
	v_mfma_f32_32x32x16_bf16 v[32:47], v[152:155], v[132:135], v[32:47]
	ds_read_b64_tr_b16 v[148:149], v207 offset:45120
	ds_read_b64_tr_b16 v[150:151], v207 offset:47680
	v_exp_f32_e32 v73, v73
	v_exp_f32_e32 v74, v74
	v_add_f32_e32 v92, v92, v93
	v_add_f32_e32 v94, v94, v95
	s_waitcnt lgkmcnt(6)
	v_mfma_f32_32x32x16_bf16 v[16:31], v[156:159], v[132:135], v[16:31]
	ds_read_b64_tr_b16 v[152:153], v207 offset:45184
	ds_read_b64_tr_b16 v[154:155], v207 offset:47744
	v_exp_f32_e32 v75, v75
	v_exp_f32_e32 v76, v76
	v_add_f32_e32 v80, v80, v82
	v_add_f32_e32 v84, v84, v86
	s_waitcnt lgkmcnt(6)
	v_mfma_f32_32x32x16_bf16 v[0:15], v[228:231], v[132:135], v[0:15]
	ds_read_b64_tr_b16 v[156:157], v207 offset:45248
	ds_read_b64_tr_b16 v[158:159], v207 offset:47808
	v_exp_f32_e32 v77, v77
	v_exp_f32_e32 v78, v78
	v_add_f32_e32 v88, v88, v90
	v_add_f32_e32 v92, v92, v94
	s_waitcnt vmcnt(3)
	ds_write_b128 v192, v[176:179]
	s_waitcnt lgkmcnt(7)
	v_mfma_f32_32x32x16_bf16 v[48:63], v[144:147], v[136:139], v[48:63]
	ds_read_b64_tr_b16 v[228:229], v207 offset:50176
	ds_read_b64_tr_b16 v[230:231], v207 offset:52736
	v_exp_f32_e32 v79, v79
	v_cvt_pk_bf16_f32 v140, v72, v73
	v_cvt_pk_bf16_f32 v141, v74, v75
	v_cvt_pk_bf16_f32 v142, v76, v77
	s_waitcnt vmcnt(2)
	ds_write_b128 v215, v[180:183]
	s_waitcnt lgkmcnt(8)
	v_mfma_f32_32x32x16_bf16 v[32:47], v[148:151], v[136:139], v[32:47]
	ds_read_b64_tr_b16 v[144:145], v207 offset:50240
	ds_read_b64_tr_b16 v[146:147], v207 offset:52800
	v_cvt_pk_bf16_f32 v143, v78, v79
	v_add_f32_e32 v80, v80, v84
	v_add_f32_e32 v88, v88, v92
	v_add_f32_e32 v64, v64, v65
	v_add_f32_e32 v66, v66, v67
	s_waitcnt vmcnt(1)
	ds_write_b128 v238, v[184:187] offset:55296
	s_waitcnt lgkmcnt(9)
	v_mfma_f32_32x32x16_bf16 v[16:31], v[152:155], v[136:139], v[16:31]
	ds_read_b64_tr_b16 v[148:149], v207 offset:50304
	ds_read_b64_tr_b16 v[150:151], v207 offset:52864
	v_add_f32_e32 v80, v80, v88
	v_add_f32_e32 v68, v68, v69
	v_add_f32_e32 v70, v70, v71
	v_add_f32_e32 v64, v64, v66
	v_add_f32_e32 v68, v68, v70
	v_add_f32_e32 v72, v72, v73
	s_waitcnt vmcnt(0)
	ds_write_b128 v239, v[188:191] offset:55296
	s_waitcnt lgkmcnt(10)
	v_mfma_f32_32x32x16_bf16 v[0:15], v[156:159], v[136:139], v[0:15]
	ds_read_b64_tr_b16 v[152:153], v207 offset:50368
	ds_read_b64_tr_b16 v[154:155], v207 offset:52928
	v_add_f32_e32 v64, v64, v68
	v_add_f32_e32 v74, v74, v75
	v_add_f32_e32 v76, v76, v77
	v_add_f32_e32 v78, v78, v79
	v_add_f32_e32 v72, v72, v74
	v_add_f32_e32 v76, v76, v78
	s_waitcnt lgkmcnt(9)
	v_mfma_f32_32x32x16_bf16 v[48:63], v[228:231], v[140:143], v[48:63]
	v_add_f32_e32 v72, v72, v76
	v_add_f32_e32 v64, v64, v72
	v_add_f32_e32 v64, v64, v80
	s_waitcnt lgkmcnt(6)
	v_mfma_f32_32x32x16_bf16 v[32:47], v[144:147], v[140:143], v[32:47]
	v_add_f32_e32 v246, v246, v64

.LBB0_748:
	s_or_b32 s24, s17, 1
	s_cmp_gt_u32 s24, 30
	s_cbranch_scc1 .LBB0_750
	ds_read_b128 v[64:67], v240
	ds_read_b128 v[144:147], v240 offset:8704
	ds_read_b128 v[156:159], v240 offset:32
	ds_read_b128 v[228:231], v240 offset:8736
	v_mfma_f32_32x32x16_bf16 v[16:31], v[148:151], v[140:143], v[16:31]
	v_mfma_f32_32x32x16_bf16 v[0:15], v[152:155], v[140:143], v[0:15]
	ds_read_b128 v[148:151], v240 offset:64
	ds_read_b128 v[152:155], v240 offset:8768
	global_load_dwordx4 v[184:187], v253, s[100:101]
	global_load_dwordx4 v[188:191], v245, s[100:101]
	s_waitcnt lgkmcnt(5)
	v_mfma_f32_32x32x16_bf16 v[80:95], v[64:67], v[160:163], 0
	v_exp_f32_e32 v112, v112
	v_exp_f32_e32 v113, v113
	s_waitcnt lgkmcnt(4)
	v_mfma_f32_32x32x16_bf16 v[64:79], v[144:147], v[160:163], 0
	ds_read_b128 v[144:147], v240 offset:96
	v_exp_f32_e32 v114, v114
	v_exp_f32_e32 v115, v115
	s_waitcnt lgkmcnt(4)
	v_mfma_f32_32x32x16_bf16 v[80:95], v[156:159], v[164:167], v[80:95]
	ds_read_b128 v[156:159], v240 offset:8800
	v_exp_f32_e32 v116, v116
	v_exp_f32_e32 v117, v117
	s_waitcnt lgkmcnt(4)
	v_mfma_f32_32x32x16_bf16 v[64:79], v[228:231], v[164:167], v[64:79]
	v_exp_f32_e32 v118, v118
	v_exp_f32_e32 v119, v119
	v_cvt_pk_bf16_f32 v128, v112, v113
	v_cvt_pk_bf16_f32 v129, v114, v115
	s_waitcnt lgkmcnt(3)
	v_mfma_f32_32x32x16_bf16 v[80:95], v[148:151], v[168:171], v[80:95]
	ds_read_b64_tr_b16 v[228:229], v207 offset:55296
	ds_read_b64_tr_b16 v[230:231], v207 offset:57856
	v_exp_f32_e32 v120, v120
	v_exp_f32_e32 v121, v121
	v_cvt_pk_bf16_f32 v130, v116, v117
	v_cvt_pk_bf16_f32 v131, v118, v119
	s_waitcnt lgkmcnt(4)
	v_mfma_f32_32x32x16_bf16 v[64:79], v[152:155], v[168:171], v[64:79]
	ds_read_b64_tr_b16 v[148:149], v207 offset:55360
	ds_read_b64_tr_b16 v[150:151], v207 offset:57920
	v_exp_f32_e32 v122, v122
	v_exp_f32_e32 v123, v123
	s_waitcnt lgkmcnt(5)
	v_mfma_f32_32x32x16_bf16 v[80:95], v[144:147], v[172:175], v[80:95]
	ds_read_b64_tr_b16 v[152:153], v207 offset:55424
	ds_read_b64_tr_b16 v[154:155], v207 offset:57984
	v_exp_f32_e32 v124, v124
	v_exp_f32_e32 v125, v125
	s_waitcnt lgkmcnt(6)
	v_mfma_f32_32x32x16_bf16 v[64:79], v[156:159], v[172:175], v[64:79]
	ds_read_b64_tr_b16 v[144:145], v207 offset:55488
	ds_read_b64_tr_b16 v[146:147], v207 offset:58048
	v_exp_f32_e32 v126, v126
	v_exp_f32_e32 v127, v127
	v_cvt_pk_bf16_f32 v132, v120, v121
	v_cvt_pk_bf16_f32 v133, v122, v123
	s_branch .LBB0_751
.LBB0_750:
	v_mfma_f32_32x32x16_bf16 v[16:31], v[148:151], v[140:143], v[16:31]
	v_mfma_f32_32x32x16_bf16 v[0:15], v[152:155], v[140:143], v[0:15]
	ds_read_b64_tr_b16 v[228:229], v207 offset:55296
	ds_read_b64_tr_b16 v[230:231], v207 offset:57856
	ds_read_b64_tr_b16 v[148:149], v207 offset:55360
	ds_read_b64_tr_b16 v[150:151], v207 offset:57920
	ds_read_b64_tr_b16 v[152:153], v207 offset:55424
	ds_read_b64_tr_b16 v[154:155], v207 offset:57984
	ds_read_b64_tr_b16 v[144:145], v207 offset:55488
	ds_read_b64_tr_b16 v[146:147], v207 offset:58048
	v_exp_f32_e32 v112, v112
	v_exp_f32_e32 v113, v113
	v_exp_f32_e32 v114, v114
	v_exp_f32_e32 v115, v115
	v_exp_f32_e32 v116, v116
	v_exp_f32_e32 v117, v117
	v_exp_f32_e32 v118, v118
	v_exp_f32_e32 v119, v119
	v_cvt_pk_bf16_f32 v128, v112, v113
	v_cvt_pk_bf16_f32 v129, v114, v115
	v_cvt_pk_bf16_f32 v130, v116, v117
	v_cvt_pk_bf16_f32 v131, v118, v119
	v_exp_f32_e32 v120, v120
	v_exp_f32_e32 v121, v121
	v_exp_f32_e32 v122, v122
	v_exp_f32_e32 v123, v123
	v_exp_f32_e32 v124, v124
	v_exp_f32_e32 v125, v125
	v_exp_f32_e32 v126, v126
	v_exp_f32_e32 v127, v127
	v_cvt_pk_bf16_f32 v132, v120, v121
	v_cvt_pk_bf16_f32 v133, v122, v123
.LBB0_751:
	s_waitcnt lgkmcnt(6)
	v_mfma_f32_32x32x16_bf16 v[48:63], v[228:231], v[128:131], v[48:63]
	ds_read_b64_tr_b16 v[156:157], v207 offset:60416
	ds_read_b64_tr_b16 v[158:159], v207 offset:62976
	v_cvt_pk_bf16_f32 v134, v124, v125
	v_cvt_pk_bf16_f32 v135, v126, v127
	v_exp_f32_e32 v96, v96
	v_exp_f32_e32 v97, v97
	s_waitcnt lgkmcnt(6)
	v_mfma_f32_32x32x16_bf16 v[32:47], v[148:151], v[128:131], v[32:47]
	ds_read_b64_tr_b16 v[228:229], v207 offset:60480
	ds_read_b64_tr_b16 v[230:231], v207 offset:63040
	v_exp_f32_e32 v98, v98
	v_exp_f32_e32 v99, v99
	v_add_f32_e32 v112, v112, v113
	v_add_f32_e32 v114, v114, v115
	s_waitcnt lgkmcnt(6)
	v_mfma_f32_32x32x16_bf16 v[16:31], v[152:155], v[128:131], v[16:31]
	ds_read_b64_tr_b16 v[148:149], v207 offset:60544
	ds_read_b64_tr_b16 v[150:151], v207 offset:63104
	v_exp_f32_e32 v100, v100
	v_exp_f32_e32 v101, v101
	v_add_f32_e32 v116, v116, v117
	v_add_f32_e32 v118, v118, v119
	s_waitcnt lgkmcnt(6)
	v_mfma_f32_32x32x16_bf16 v[0:15], v[144:147], v[128:131], v[0:15]
	ds_read_b64_tr_b16 v[152:153], v207 offset:60608
	ds_read_b64_tr_b16 v[154:155], v207 offset:63168
	v_exp_f32_e32 v102, v102
	v_exp_f32_e32 v103, v103
	v_add_f32_e32 v120, v120, v121
	v_add_f32_e32 v122, v122, v123
	s_waitcnt lgkmcnt(6)
	v_mfma_f32_32x32x16_bf16 v[48:63], v[156:159], v[132:135], v[48:63]
	ds_read_b64_tr_b16 v[144:145], v209 offset:10240
	ds_read_b64_tr_b16 v[146:147], v209 offset:12800
	v_cvt_pk_bf16_f32 v136, v96, v97
	v_cvt_pk_bf16_f32 v137, v98, v99
	v_cvt_pk_bf16_f32 v138, v100, v101
	v_cvt_pk_bf16_f32 v139, v102, v103
	v_exp_f32_e32 v104, v104
	s_waitcnt lgkmcnt(6)
	v_mfma_f32_32x32x16_bf16 v[32:47], v[228:231], v[132:135], v[32:47]
	ds_read_b64_tr_b16 v[156:157], v209 offset:10304
	ds_read_b64_tr_b16 v[158:159], v209 offset:12864
	v_exp_f32_e32 v105, v105
	v_exp_f32_e32 v106, v106
	v_add_f32_e32 v124, v124, v125
	v_add_f32_e32 v126, v126, v127
	s_waitcnt lgkmcnt(6)
	v_mfma_f32_32x32x16_bf16 v[16:31], v[148:151], v[132:135], v[16:31]
	ds_read_b64_tr_b16 v[228:229], v209 offset:10368
	ds_read_b64_tr_b16 v[230:231], v209 offset:12928
	v_exp_f32_e32 v107, v107
	v_exp_f32_e32 v108, v108
	v_add_f32_e32 v112, v112, v114
	v_add_f32_e32 v116, v116, v118
	s_waitcnt lgkmcnt(6)
	v_mfma_f32_32x32x16_bf16 v[0:15], v[152:155], v[132:135], v[0:15]
	ds_read_b64_tr_b16 v[148:149], v209 offset:10432
	ds_read_b64_tr_b16 v[150:151], v209 offset:12992
	v_exp_f32_e32 v109, v109
	v_exp_f32_e32 v110, v110
	v_add_f32_e32 v120, v120, v122
	v_add_f32_e32 v124, v124, v126
	s_waitcnt vmcnt(3)
	ds_write_b128 v241, v[176:179] offset:17408
	s_waitcnt lgkmcnt(7)
	v_mfma_f32_32x32x16_bf16 v[48:63], v[144:147], v[136:139], v[48:63]
	ds_read_b64_tr_b16 v[152:153], v209 offset:15360
	ds_read_b64_tr_b16 v[154:155], v209 offset:17920
	v_exp_f32_e32 v111, v111
	v_cvt_pk_bf16_f32 v140, v104, v105
	v_cvt_pk_bf16_f32 v141, v106, v107
	v_cvt_pk_bf16_f32 v142, v108, v109
	s_waitcnt vmcnt(2)
	ds_write_b128 v242, v[180:183] offset:17408
	s_waitcnt lgkmcnt(8)
	v_mfma_f32_32x32x16_bf16 v[32:47], v[156:159], v[136:139], v[32:47]
	ds_read_b64_tr_b16 v[144:145], v209 offset:15424
	ds_read_b64_tr_b16 v[146:147], v209 offset:17984
	v_cvt_pk_bf16_f32 v143, v110, v111
	v_add_f32_e32 v112, v112, v116
	v_add_f32_e32 v120, v120, v124
	v_add_f32_e32 v96, v96, v97
	v_add_f32_e32 v98, v98, v99
	s_waitcnt vmcnt(1)
	ds_write_b128 v243, v[184:187] offset:34816
	s_waitcnt lgkmcnt(9)
	v_mfma_f32_32x32x16_bf16 v[16:31], v[228:231], v[136:139], v[16:31]
	ds_read_b64_tr_b16 v[156:157], v209 offset:15488
	ds_read_b64_tr_b16 v[158:159], v209 offset:18048
	v_add_f32_e32 v112, v112, v120
	v_add_f32_e32 v100, v100, v101
	v_add_f32_e32 v102, v102, v103
	v_add_f32_e32 v96, v96, v98
	v_add_f32_e32 v100, v100, v102
	v_add_f32_e32 v104, v104, v105
	s_waitcnt vmcnt(0)
	ds_write_b128 v244, v[188:191] offset:34816
	s_waitcnt lgkmcnt(10)
	v_mfma_f32_32x32x16_bf16 v[0:15], v[148:151], v[136:139], v[0:15]
	ds_read_b64_tr_b16 v[228:229], v209 offset:15552
	ds_read_b64_tr_b16 v[230:231], v209 offset:18112
	v_add_f32_e32 v96, v96, v100
	v_add_f32_e32 v106, v106, v107
	v_add_f32_e32 v108, v108, v109
	v_add_f32_e32 v110, v110, v111
	v_add_f32_e32 v104, v104, v106
	v_add_f32_e32 v108, v108, v110
	s_waitcnt lgkmcnt(9)
	v_mfma_f32_32x32x16_bf16 v[48:63], v[152:155], v[140:143], v[48:63]
	v_add_f32_e32 v104, v104, v108
	v_add_f32_e32 v96, v96, v104
	v_add_f32_e32 v96, v96, v112
	s_waitcnt lgkmcnt(6)
	v_mfma_f32_32x32x16_bf16 v[32:47], v[144:147], v[140:143], v[32:47]
	v_add_f32_e32 v246, v246, v96

.LBB0_759:
	v_mfma_f32_32x32x16_bf16 v[16:31], v[156:159], v[140:143], v[16:31]
	v_mfma_f32_32x32x16_bf16 v[0:15], v[228:231], v[140:143], v[0:15]
	v_mov_b32_e32 v64, v246
	s_nop 1
	v_permlane32_swap_b32_e32 v246, v64
	v_add_f32_e32 v64, v246, v64
	v_div_scale_f32 v65, s[18:19], v64, v64, 1.0
	v_rcp_f32_e32 v66, v65
	s_nop 0
	v_fma_f32 v67, -v65, v66, 1.0
	v_fmac_f32_e32 v66, v67, v66
	v_div_scale_f32 v67, vcc, 1.0, v64, 1.0
	v_mul_f32_e32 v68, v67, v66
	v_fma_f32 v69, -v65, v68, v67
	v_fmac_f32_e32 v68, v69, v66
	v_fma_f32 v65, -v65, v68, v67
	v_div_fmas_f32 v65, v65, v66, v68
	s_andn2_b64 vcc, exec, s[14:15]
	v_div_fixup_f32 v80, v65, v64, 1.0
	s_cbranch_vccnz .LBB0_761
	v_pk_mul_f32 v[64:65], v[48:49], v[80:81] op_sel_hi:[1,0]
	v_pk_mul_f32 v[66:67], v[50:51], v[80:81] op_sel_hi:[1,0]
	v_add_u32_e32 v68, s53, v237
	ds_write_b128 v68, v[64:67]
	v_pk_mul_f32 v[64:65], v[52:53], v[80:81] op_sel_hi:[1,0]
	v_pk_mul_f32 v[66:67], v[54:55], v[80:81] op_sel_hi:[1,0]
	ds_write_b128 v68, v[64:67] offset:1024
	v_pk_mul_f32 v[64:65], v[56:57], v[80:81] op_sel_hi:[1,0]
	v_pk_mul_f32 v[66:67], v[58:59], v[80:81] op_sel_hi:[1,0]
	ds_write_b128 v68, v[64:67] offset:2048
	v_pk_mul_f32 v[64:65], v[60:61], v[80:81] op_sel_hi:[1,0]
	v_pk_mul_f32 v[66:67], v[62:63], v[80:81] op_sel_hi:[1,0]
	ds_write_b128 v68, v[64:67] offset:3072
	v_pk_mul_f32 v[64:65], v[32:33], v[80:81] op_sel_hi:[1,0]
	v_pk_mul_f32 v[66:67], v[34:35], v[80:81] op_sel_hi:[1,0]
	ds_write_b128 v68, v[64:67] offset:4096
	v_pk_mul_f32 v[64:65], v[36:37], v[80:81] op_sel_hi:[1,0]
	v_pk_mul_f32 v[66:67], v[38:39], v[80:81] op_sel_hi:[1,0]
	ds_write_b128 v68, v[64:67] offset:5120
	v_pk_mul_f32 v[64:65], v[40:41], v[80:81] op_sel_hi:[1,0]
	v_pk_mul_f32 v[66:67], v[42:43], v[80:81] op_sel_hi:[1,0]
	ds_write_b128 v68, v[64:67] offset:6144
	v_pk_mul_f32 v[64:65], v[44:45], v[80:81] op_sel_hi:[1,0]
	v_pk_mul_f32 v[66:67], v[46:47], v[80:81] op_sel_hi:[1,0]
	ds_write_b128 v68, v[64:67] offset:7168
	v_pk_mul_f32 v[64:65], v[16:17], v[80:81] op_sel_hi:[1,0]
	v_pk_mul_f32 v[66:67], v[18:19], v[80:81] op_sel_hi:[1,0]
	ds_write_b128 v68, v[64:67] offset:8192
	v_pk_mul_f32 v[64:65], v[20:21], v[80:81] op_sel_hi:[1,0]
	v_pk_mul_f32 v[66:67], v[22:23], v[80:81] op_sel_hi:[1,0]
	ds_write_b128 v68, v[64:67] offset:9216
	v_pk_mul_f32 v[64:65], v[24:25], v[80:81] op_sel_hi:[1,0]
	v_pk_mul_f32 v[66:67], v[26:27], v[80:81] op_sel_hi:[1,0]
	ds_write_b128 v68, v[64:67] offset:10240
	v_pk_mul_f32 v[64:65], v[28:29], v[80:81] op_sel_hi:[1,0]
	v_pk_mul_f32 v[66:67], v[30:31], v[80:81] op_sel_hi:[1,0]
	ds_write_b128 v68, v[64:67] offset:11264
	v_pk_mul_f32 v[64:65], v[0:1], v[80:81] op_sel_hi:[1,0]
	v_pk_mul_f32 v[66:67], v[2:3], v[80:81] op_sel_hi:[1,0]
	ds_write_b128 v68, v[64:67] offset:12288
	v_pk_mul_f32 v[64:65], v[4:5], v[80:81] op_sel_hi:[1,0]
	v_pk_mul_f32 v[66:67], v[6:7], v[80:81] op_sel_hi:[1,0]
	ds_write_b128 v68, v[64:67] offset:13312
	v_pk_mul_f32 v[64:65], v[8:9], v[80:81] op_sel_hi:[1,0]
	v_pk_mul_f32 v[66:67], v[10:11], v[80:81] op_sel_hi:[1,0]
	ds_write_b128 v68, v[64:67] offset:14336
	v_pk_mul_f32 v[64:65], v[12:13], v[80:81] op_sel_hi:[1,0]
	v_pk_mul_f32 v[66:67], v[14:15], v[80:81] op_sel_hi:[1,0]
	ds_write_b128 v68, v[64:67] offset:15360

.LBB0_2799:
	s_lshl_b32 s8, s56, 5
	s_add_i32 s8, s8, s55
	v_readlane_b32 s18, v254, 6
	s_or_b32 s8, s8, s54
	v_readlane_b32 s19, v254, 7
	s_and_b64 s[18:19], s[18:19], exec
	s_cselect_b32 s58, s8, s45
	s_ashr_i32 s18, s58, 6
	s_lshl_b32 s8, s58, 7
	s_ashr_i32 s19, s18, 31
	s_and_b32 s8, s8, 0x780
	s_lshl_b64 s[38:39], s[18:19], 20
	s_lshl_b64 s[40:41], s[18:19], 21
	s_add_u32 s17, s12, s40
	s_addc_u32 s18, s13, s41
	s_lshl_b32 s19, s58, 3
	s_and_b32 s57, s19, 0x180
	s_lshl_b32 s22, s57, 1
	s_add_u32 s17, s17, s22
	s_addc_u32 s19, s18, 0
	s_add_u32 s18, s17, s36
	s_addc_u32 s19, s19, s37
	s_add_u32 s17, s48, s40
	s_addc_u32 s21, s49, s41
	s_add_u32 s20, s17, s22
	s_addc_u32 s21, s21, 0
	s_add_u32 s17, s50, s40
	s_addc_u32 s23, s51, s41
	s_add_u32 s22, s17, s22
	s_addc_u32 s23, s23, 0
	v_lshl_add_u64 v[0:1], s[20:21], 0, v[216:217]
	v_lshl_add_u64 v[2:3], s[20:21], 0, v[220:221]
	v_lshl_add_u64 v[8:9], s[22:23], 0, v[216:217]
	v_lshl_add_u64 v[10:11], s[22:23], 0, v[220:221]
	v_lshl_add_u64 v[0:1], v[0:1], 0, v[218:219]
	v_lshl_add_u64 v[4:5], v[2:3], 0, v[222:223]
	v_lshl_add_u64 v[8:9], v[8:9], 0, v[218:219]
	v_lshl_add_u64 v[12:13], v[10:11], 0, v[222:223]
	global_load_dwordx4 v[0:3], v[0:1], off
	s_nop 0
	global_load_dwordx4 v[4:7], v[4:5], off
	s_nop 0
	global_load_dwordx4 v[8:11], v[8:9], off
	s_nop 0
	global_load_dwordx4 v[12:15], v[12:13], off
	v_or_b32_e32 v16, s8, v233
	v_lshlrev_b32_e32 v192, 10, v16
	v_lshl_add_u64 v[16:17], s[18:19], 0, v[192:193]
	v_mov_b32_e32 v215, v193
	v_lshl_add_u64 v[16:17], v[16:17], 0, v[214:215]
	global_load_dwordx4 v[160:163], v[16:17], off
	global_load_dwordx4 v[164:167], v[16:17], off offset:32
	global_load_dwordx4 v[168:171], v[16:17], off offset:64
	global_load_dwordx4 v[172:175], v[16:17], off offset:96
	v_lshl_add_u64 v[16:17], s[20:21], 0, v[196:197]
	v_lshl_add_u64 v[18:19], s[20:21], 0, v[198:199]
	v_lshl_add_u64 v[16:17], v[16:17], 0, v[218:219]
	v_lshl_add_u64 v[18:19], v[18:19], 0, v[222:223]
	global_load_dwordx4 v[176:179], v[16:17], off
	global_load_dwordx4 v[180:183], v[18:19], off
	v_add_u32_e32 v192, v202, v234
	v_add_u32_e32 v215, v204, v235
	v_add_u32_e32 v243, v206, v234
	v_add_u32_e32 v244, v208, v235
	s_mov_b32 s17, s16
	s_mov_b32 s18, s16
	s_mov_b32 s19, s16
	s_mov_b32 s20, s16
	s_mov_b32 s21, s16
	s_mov_b32 s22, s16
	s_mov_b32 s23, s16
	s_mov_b32 s24, s16
	s_mov_b32 s25, s16
	s_mov_b32 s26, s16
	s_mov_b32 s27, s16
	s_mov_b32 s28, s16
	s_mov_b32 s29, s16
	s_mov_b32 s30, s16
	s_mov_b32 s31, s16
	v_mov_b32_e32 v246, 0
	v_mov_b32_e32 v245, 0xf149f2ca
	s_waitcnt vmcnt(9)
	ds_write_b128 v192, v[0:3]
	s_waitcnt vmcnt(8)
	ds_write_b128 v215, v[4:7]
	s_waitcnt vmcnt(7)
	ds_write_b128 v243, v[8:11] offset:34816
	s_waitcnt vmcnt(6)
	ds_write_b128 v244, v[12:15] offset:34816
	s_waitcnt lgkmcnt(0)
	s_barrier
	ds_read_b128 v[0:3], v240
	ds_read_b128 v[4:7], v240 offset:32
	s_waitcnt vmcnt(5) lgkmcnt(1)
	v_mfma_f32_32x32x16_bf16 v[80:95], v[0:3], v[160:163], 0
	ds_read_b128 v[0:3], v240 offset:8704
	ds_read_b128 v[8:11], v240 offset:8736
	s_waitcnt lgkmcnt(1)
	v_mfma_f32_32x32x16_bf16 v[64:79], v[0:3], v[160:163], 0
	ds_read_b128 v[0:3], v240 offset:64
	s_waitcnt vmcnt(4)
	v_mfma_f32_32x32x16_bf16 v[80:95], v[4:7], v[164:167], v[80:95]
	ds_read_b128 v[4:7], v240 offset:8768
	ds_read_b128 v[16:19], v240 offset:96
	ds_read_b128 v[20:23], v240 offset:8800
	s_waitcnt vmcnt(1)
	ds_write_b128 v241, v[176:179] offset:17408
	s_waitcnt vmcnt(0)
	ds_write_b128 v242, v[180:183] offset:17408
	s_waitcnt lgkmcnt(0)
	s_barrier
	v_mfma_f32_32x32x16_bf16 v[64:79], v[8:11], v[164:167], v[64:79]
	v_mfma_f32_32x32x16_bf16 v[80:95], v[0:3], v[168:171], v[80:95]
	v_mfma_f32_32x32x16_bf16 v[64:79], v[4:7], v[168:171], v[64:79]
	v_mov_b64_e32 v[0:1], s[16:17]
	v_mov_b64_e32 v[2:3], s[18:19]
	v_mov_b64_e32 v[4:5], s[20:21]
	v_mov_b64_e32 v[6:7], s[22:23]
	v_mov_b64_e32 v[8:9], s[24:25]
	v_mov_b64_e32 v[10:11], s[26:27]
	v_mov_b64_e32 v[12:13], s[28:29]
	v_mfma_f32_32x32x16_bf16 v[80:95], v[16:19], v[172:175], v[80:95]
	v_mov_b64_e32 v[14:15], s[30:31]
	s_lshl_b32 s17, s58, 4
	s_and_b32 s17, s17, 0x300
	s_or_b32 s40, s40, s17
	v_mov_b64_e32 v[46:47], v[14:15]
	v_mov_b64_e32 v[62:63], v[14:15]
	v_lshl_add_u64 v[224:225], v[210:211], 0, s[40:41]
	v_mfma_f32_32x32x16_bf16 v[64:79], v[20:23], v[172:175], v[64:79]
	v_mov_b64_e32 v[30:31], v[14:15]
	v_lshl_add_u64 v[226:227], v[212:213], 0, s[40:41]
	s_mov_b64 s[18:19], 0
	v_mov_b64_e32 v[28:29], v[12:13]
	v_mov_b64_e32 v[26:27], v[10:11]
	v_mov_b64_e32 v[24:25], v[8:9]
	v_mov_b64_e32 v[22:23], v[6:7]
	v_mov_b64_e32 v[20:21], v[4:5]
	v_mov_b64_e32 v[18:19], v[2:3]
	v_mov_b64_e32 v[16:17], v[0:1]
	v_mov_b64_e32 v[44:45], v[12:13]
	v_mov_b64_e32 v[42:43], v[10:11]
	v_mov_b64_e32 v[40:41], v[8:9]
	v_mov_b64_e32 v[38:39], v[6:7]
	v_mov_b64_e32 v[36:37], v[4:5]
	v_mov_b64_e32 v[34:35], v[2:3]
	v_mov_b64_e32 v[32:33], v[0:1]
	v_mov_b64_e32 v[60:61], v[12:13]
	v_mov_b64_e32 v[58:59], v[10:11]
	v_mov_b64_e32 v[56:57], v[8:9]
	v_mov_b64_e32 v[54:55], v[6:7]
	v_mov_b64_e32 v[52:53], v[4:5]
	v_mov_b64_e32 v[50:51], v[2:3]
	v_mov_b64_e32 v[48:49], v[0:1]
	v_readfirstlane_b32 s98, v226
	v_readfirstlane_b32 s99, v227
	s_nop 3
	v_subrev_u32_e32 v247, s98, v226
	v_add_u32_e32 v252, 0x8000, v247
	v_add_u32_e32 v253, 0x10000, v247
	v_add_u32_e32 v245, 0x18000, v247
	s_add_u32 s100, s98, 0xbf10000
	s_addc_u32 s101, s99, 0
	s_add_u32 s98, s98, 0xaf20000
	s_addc_u32 s99, s99, 0
	s_mov_b32 s17, 0
	v_mov_b32_e32 v140, 0
	v_mov_b32_e32 v141, 0
	v_mov_b32_e32 v142, 0
	v_mov_b32_e32 v143, 0
	v_mov_b32_e32 v156, 0
	v_mov_b32_e32 v157, 0
	v_mov_b32_e32 v158, 0
	v_mov_b32_e32 v159, 0
	v_mov_b32_e32 v228, 0
	v_mov_b32_e32 v229, 0
	v_mov_b32_e32 v230, 0
	v_mov_b32_e32 v231, 0
